# align8: code placement - every 8-byte instruction of the hand-scheduled scanner loop sits on an 8-byte boundary (loop head .p2align 3, 4-byte ops paired with s_nop or promoted to e64)
# speedup vs baseline: 1.0082x; 1.0082x over previous
.LBB0_724:
	s_and_b32 s16, s59, 3
	s_and_saveexec_b64 s[0:1], s[2:3]
	s_xor_b64 s[8:9], exec, s[0:1]
	s_cbranch_execz .LBB0_727
	v_mov_b32_e32 v2, 0
	v_lshl_add_u32 v0, s16, 6, v41
	s_mov_b32 s0, 0
	v_mov_b32_e32 v3, v2
	v_mov_b32_e32 v4, v2
	v_mov_b32_e32 v5, v2
	s_barrier
	.p2align 3
.LBB0_726:
	s_and_b32 s1, s0, 1
	s_lshl_b32 s31, s1, 8
	s_mul_i32 s30, s1, 0xa000
	s_add_i32 s31, s31, 0x18000
	v_add_u32_e32 v6, s30, v151
	v_mov_b32_e32 v8, s31
	v_lshl_add_u32 v7, s1, 13, v0
	v_lshl_add_u32 v9, s1, 11, v39
	v_add_u32_e32 v22, 0x400, v9
	ds_read_b128 v[58:61], v6
	ds_read_b128 v[62:65], v6 offset:16
	ds_read_b128 v[66:69], v6 offset:32
	ds_read_b128 v[70:73], v6 offset:48
	ds_read_b128 v[74:77], v6 offset:64
	ds_read2st64_b32 v[118:119], v7 offset1:1
	ds_read_b64 v[120:121], v8
	ds_read_b128 v[78:81], v6 offset:1280
	ds_read_b128 v[82:85], v6 offset:1296
	ds_read_b128 v[86:89], v6 offset:1312
	ds_read_b128 v[90:93], v6 offset:1328
	ds_read_b128 v[94:97], v6 offset:1344
	ds_read_b128 v[98:101], v6 offset:2560
	ds_read_b128 v[102:105], v6 offset:2576
	ds_read_b128 v[106:109], v6 offset:2592
	ds_read_b128 v[110:113], v6 offset:2608
	ds_read_b128 v[114:117], v6 offset:2624
	ds_read2st64_b32 v[206:207], v7 offset0:2 offset1:3
	ds_read_b64 v[208:209], v8 offset:8
	s_waitcnt lgkmcnt(12)
	s_nop 0
	v_pk_mul_f32 v[10:11], v[2:3], v[58:59] op_sel_hi:[0,1]
	v_pk_fma_f32 v[10:11], v[2:3], v[60:61], v[10:11] op_sel:[1,0,0] op_sel_hi:[1,1,1]
	v_pk_fma_f32 v[10:11], v[4:5], v[62:63], v[10:11] op_sel_hi:[0,1,1]
	v_pk_fma_f32 v[10:11], v[4:5], v[64:65], v[10:11] op_sel:[1,0,0] op_sel_hi:[1,1,1]
	v_pk_mul_f32 v[18:19], v[74:75], v[118:119] op_sel_hi:[1,0]
	v_pk_mul_f32 v[20:21], v[76:77], v[118:119] op_sel_hi:[1,0]
	v_add_f32_dpp v10, v10, v10 quad_perm:[1,0,3,2] row_mask:0xf bank_mask:0xf bound_ctrl:1
	v_add_f32_dpp v11, v11, v11 quad_perm:[1,0,3,2] row_mask:0xf bank_mask:0xf bound_ctrl:1
	v_pk_fma_f32 v[18:19], v[2:3], v[66:67], v[18:19]
	v_add_f32_dpp v10, v10, v10 quad_perm:[2,3,0,1] row_mask:0xf bank_mask:0xf bound_ctrl:1
	v_add_f32_dpp v11, v11, v11 quad_perm:[2,3,0,1] row_mask:0xf bank_mask:0xf bound_ctrl:1
	v_pk_fma_f32 v[20:21], v[4:5], v[68:69], v[20:21]
	v_add_f32_dpp v10, v10, v10 row_half_mirror row_mask:0xf bank_mask:0xf bound_ctrl:1
	v_add_f32_dpp v11, v11, v11 row_half_mirror row_mask:0xf bank_mask:0xf bound_ctrl:1
	s_nop 0
	s_nop 0
	v_add_f32_dpp v10, v10, v10 row_mirror row_mask:0xf bank_mask:0xf bound_ctrl:1
	v_add_f32_dpp v11, v11, v11 row_mirror row_mask:0xf bank_mask:0xf bound_ctrl:1
	v_pk_fma_f32 v[2:3], v[70:71], v[10:11], v[18:19] op_sel_hi:[1,0,1]
	v_pk_fma_f32 v[4:5], v[72:73], v[10:11], v[20:21] op_sel_hi:[1,0,1]
	v_fmac_f32_e64 v11, v120, v10
	ds_read_b128 v[186:189], v6 offset:3840
	ds_read_b128 v[190:193], v6 offset:3856
	ds_read_b128 v[194:197], v6 offset:3872
	ds_read_b128 v[198:201], v6 offset:3888
	ds_read_b128 v[202:205], v6 offset:3904
	s_waitcnt lgkmcnt(12)
	s_nop 0
	v_pk_mul_f32 v[12:13], v[2:3], v[78:79] op_sel_hi:[0,1]
	v_pk_fma_f32 v[12:13], v[2:3], v[80:81], v[12:13] op_sel:[1,0,0] op_sel_hi:[1,1,1]
	v_pk_fma_f32 v[12:13], v[4:5], v[82:83], v[12:13] op_sel_hi:[0,1,1]
	v_pk_fma_f32 v[12:13], v[4:5], v[84:85], v[12:13] op_sel:[1,0,0] op_sel_hi:[1,1,1]
	v_pk_mul_f32 v[18:19], v[94:95], v[118:119] op_sel:[0,1] op_sel_hi:[1,1]
	v_pk_mul_f32 v[20:21], v[96:97], v[118:119] op_sel:[0,1] op_sel_hi:[1,1]
	v_add_f32_dpp v12, v12, v12 quad_perm:[1,0,3,2] row_mask:0xf bank_mask:0xf bound_ctrl:1
	v_add_f32_dpp v13, v13, v13 quad_perm:[1,0,3,2] row_mask:0xf bank_mask:0xf bound_ctrl:1
	v_pk_fma_f32 v[18:19], v[2:3], v[86:87], v[18:19]
	v_add_f32_dpp v12, v12, v12 quad_perm:[2,3,0,1] row_mask:0xf bank_mask:0xf bound_ctrl:1
	v_add_f32_dpp v13, v13, v13 quad_perm:[2,3,0,1] row_mask:0xf bank_mask:0xf bound_ctrl:1
	v_pk_fma_f32 v[20:21], v[4:5], v[88:89], v[20:21]
	v_add_f32_dpp v12, v12, v12 row_half_mirror row_mask:0xf bank_mask:0xf bound_ctrl:1
	v_add_f32_dpp v13, v13, v13 row_half_mirror row_mask:0xf bank_mask:0xf bound_ctrl:1
	s_nop 0
	s_nop 0
	v_add_f32_dpp v12, v12, v12 row_mirror row_mask:0xf bank_mask:0xf bound_ctrl:1
	v_add_f32_dpp v13, v13, v13 row_mirror row_mask:0xf bank_mask:0xf bound_ctrl:1
	v_pk_fma_f32 v[2:3], v[90:91], v[12:13], v[18:19] op_sel_hi:[1,0,1]
	v_pk_fma_f32 v[4:5], v[92:93], v[12:13], v[20:21] op_sel_hi:[1,0,1]
	v_fmac_f32_e64 v13, v121, v12
	ds_write2_b32 v9, v11, v13 offset1:16
	ds_read_b128 v[58:61], v6 offset:5120
	ds_read_b128 v[62:65], v6 offset:5136
	ds_read_b128 v[66:69], v6 offset:5152
	ds_read_b128 v[70:73], v6 offset:5168
	ds_read_b128 v[74:77], v6 offset:5184
	ds_read2st64_b32 v[118:119], v7 offset0:4 offset1:5
	ds_read_b64 v[120:121], v8 offset:16
	s_waitcnt lgkmcnt(13)
	s_nop 0
	v_pk_mul_f32 v[14:15], v[2:3], v[98:99] op_sel_hi:[0,1]
	v_pk_fma_f32 v[14:15], v[2:3], v[100:101], v[14:15] op_sel:[1,0,0] op_sel_hi:[1,1,1]
	v_pk_fma_f32 v[14:15], v[4:5], v[102:103], v[14:15] op_sel_hi:[0,1,1]
	v_pk_fma_f32 v[14:15], v[4:5], v[104:105], v[14:15] op_sel:[1,0,0] op_sel_hi:[1,1,1]
	v_pk_mul_f32 v[18:19], v[114:115], v[206:207] op_sel_hi:[1,0]
	v_pk_mul_f32 v[20:21], v[116:117], v[206:207] op_sel_hi:[1,0]
	v_add_f32_dpp v14, v14, v14 quad_perm:[1,0,3,2] row_mask:0xf bank_mask:0xf bound_ctrl:1
	v_add_f32_dpp v15, v15, v15 quad_perm:[1,0,3,2] row_mask:0xf bank_mask:0xf bound_ctrl:1
	v_pk_fma_f32 v[18:19], v[2:3], v[106:107], v[18:19]
	v_add_f32_dpp v14, v14, v14 quad_perm:[2,3,0,1] row_mask:0xf bank_mask:0xf bound_ctrl:1
	v_add_f32_dpp v15, v15, v15 quad_perm:[2,3,0,1] row_mask:0xf bank_mask:0xf bound_ctrl:1
	v_pk_fma_f32 v[20:21], v[4:5], v[108:109], v[20:21]
	v_add_f32_dpp v14, v14, v14 row_half_mirror row_mask:0xf bank_mask:0xf bound_ctrl:1
	v_add_f32_dpp v15, v15, v15 row_half_mirror row_mask:0xf bank_mask:0xf bound_ctrl:1
	s_nop 0
	s_nop 0
	v_add_f32_dpp v14, v14, v14 row_mirror row_mask:0xf bank_mask:0xf bound_ctrl:1
	v_add_f32_dpp v15, v15, v15 row_mirror row_mask:0xf bank_mask:0xf bound_ctrl:1
	v_pk_fma_f32 v[2:3], v[110:111], v[14:15], v[18:19] op_sel_hi:[1,0,1]
	v_pk_fma_f32 v[4:5], v[112:113], v[14:15], v[20:21] op_sel_hi:[1,0,1]
	v_fmac_f32_e64 v15, v208, v14
	ds_read_b128 v[78:81], v6 offset:6400
	ds_read_b128 v[82:85], v6 offset:6416
	ds_read_b128 v[86:89], v6 offset:6432
	ds_read_b128 v[90:93], v6 offset:6448
	ds_read_b128 v[94:97], v6 offset:6464
	s_waitcnt lgkmcnt(13)
	s_nop 0
	v_pk_mul_f32 v[16:17], v[2:3], v[186:187] op_sel_hi:[0,1]
	v_pk_fma_f32 v[16:17], v[2:3], v[188:189], v[16:17] op_sel:[1,0,0] op_sel_hi:[1,1,1]
	v_pk_fma_f32 v[16:17], v[4:5], v[190:191], v[16:17] op_sel_hi:[0,1,1]
	v_pk_fma_f32 v[16:17], v[4:5], v[192:193], v[16:17] op_sel:[1,0,0] op_sel_hi:[1,1,1]
	v_pk_mul_f32 v[18:19], v[202:203], v[206:207] op_sel:[0,1] op_sel_hi:[1,1]
	v_pk_mul_f32 v[20:21], v[204:205], v[206:207] op_sel:[0,1] op_sel_hi:[1,1]
	v_add_f32_dpp v16, v16, v16 quad_perm:[1,0,3,2] row_mask:0xf bank_mask:0xf bound_ctrl:1
	v_add_f32_dpp v17, v17, v17 quad_perm:[1,0,3,2] row_mask:0xf bank_mask:0xf bound_ctrl:1
	v_pk_fma_f32 v[18:19], v[2:3], v[194:195], v[18:19]
	v_add_f32_dpp v16, v16, v16 quad_perm:[2,3,0,1] row_mask:0xf bank_mask:0xf bound_ctrl:1
	v_add_f32_dpp v17, v17, v17 quad_perm:[2,3,0,1] row_mask:0xf bank_mask:0xf bound_ctrl:1
	v_pk_fma_f32 v[20:21], v[4:5], v[196:197], v[20:21]
	v_add_f32_dpp v16, v16, v16 row_half_mirror row_mask:0xf bank_mask:0xf bound_ctrl:1
	v_add_f32_dpp v17, v17, v17 row_half_mirror row_mask:0xf bank_mask:0xf bound_ctrl:1
	s_nop 0
	s_nop 0
	v_add_f32_dpp v16, v16, v16 row_mirror row_mask:0xf bank_mask:0xf bound_ctrl:1
	v_add_f32_dpp v17, v17, v17 row_mirror row_mask:0xf bank_mask:0xf bound_ctrl:1
	v_pk_fma_f32 v[2:3], v[198:199], v[16:17], v[18:19] op_sel_hi:[1,0,1]
	v_pk_fma_f32 v[4:5], v[200:201], v[16:17], v[20:21] op_sel_hi:[1,0,1]
	v_fmac_f32_e64 v17, v209, v16
	ds_write2_b32 v9, v15, v17 offset0:32 offset1:48
	ds_read_b128 v[98:101], v6 offset:7680
	ds_read_b128 v[102:105], v6 offset:7696
	ds_read_b128 v[106:109], v6 offset:7712
	ds_read_b128 v[110:113], v6 offset:7728
	ds_read_b128 v[114:117], v6 offset:7744
	ds_read2st64_b32 v[206:207], v7 offset0:6 offset1:7
	ds_read_b64 v[208:209], v8 offset:24
	s_waitcnt lgkmcnt(13)
	s_nop 0
	v_pk_mul_f32 v[10:11], v[2:3], v[58:59] op_sel_hi:[0,1]
	v_pk_fma_f32 v[10:11], v[2:3], v[60:61], v[10:11] op_sel:[1,0,0] op_sel_hi:[1,1,1]
	v_pk_fma_f32 v[10:11], v[4:5], v[62:63], v[10:11] op_sel_hi:[0,1,1]
	v_pk_fma_f32 v[10:11], v[4:5], v[64:65], v[10:11] op_sel:[1,0,0] op_sel_hi:[1,1,1]
	v_pk_mul_f32 v[18:19], v[74:75], v[118:119] op_sel_hi:[1,0]
	v_pk_mul_f32 v[20:21], v[76:77], v[118:119] op_sel_hi:[1,0]
	v_add_f32_dpp v10, v10, v10 quad_perm:[1,0,3,2] row_mask:0xf bank_mask:0xf bound_ctrl:1
	v_add_f32_dpp v11, v11, v11 quad_perm:[1,0,3,2] row_mask:0xf bank_mask:0xf bound_ctrl:1
	v_pk_fma_f32 v[18:19], v[2:3], v[66:67], v[18:19]
	v_add_f32_dpp v10, v10, v10 quad_perm:[2,3,0,1] row_mask:0xf bank_mask:0xf bound_ctrl:1
	v_add_f32_dpp v11, v11, v11 quad_perm:[2,3,0,1] row_mask:0xf bank_mask:0xf bound_ctrl:1
	v_pk_fma_f32 v[20:21], v[4:5], v[68:69], v[20:21]
	v_add_f32_dpp v10, v10, v10 row_half_mirror row_mask:0xf bank_mask:0xf bound_ctrl:1
	v_add_f32_dpp v11, v11, v11 row_half_mirror row_mask:0xf bank_mask:0xf bound_ctrl:1
	s_nop 0
	s_nop 0
	v_add_f32_dpp v10, v10, v10 row_mirror row_mask:0xf bank_mask:0xf bound_ctrl:1
	v_add_f32_dpp v11, v11, v11 row_mirror row_mask:0xf bank_mask:0xf bound_ctrl:1
	v_pk_fma_f32 v[2:3], v[70:71], v[10:11], v[18:19] op_sel_hi:[1,0,1]
	v_pk_fma_f32 v[4:5], v[72:73], v[10:11], v[20:21] op_sel_hi:[1,0,1]
	v_fmac_f32_e64 v11, v120, v10
	ds_read_b128 v[186:189], v6 offset:8960
	ds_read_b128 v[190:193], v6 offset:8976
	ds_read_b128 v[194:197], v6 offset:8992
	ds_read_b128 v[198:201], v6 offset:9008
	ds_read_b128 v[202:205], v6 offset:9024
	s_waitcnt lgkmcnt(13)
	s_nop 0
	v_pk_mul_f32 v[12:13], v[2:3], v[78:79] op_sel_hi:[0,1]
	v_pk_fma_f32 v[12:13], v[2:3], v[80:81], v[12:13] op_sel:[1,0,0] op_sel_hi:[1,1,1]
	v_pk_fma_f32 v[12:13], v[4:5], v[82:83], v[12:13] op_sel_hi:[0,1,1]
	v_pk_fma_f32 v[12:13], v[4:5], v[84:85], v[12:13] op_sel:[1,0,0] op_sel_hi:[1,1,1]
	v_pk_mul_f32 v[18:19], v[94:95], v[118:119] op_sel:[0,1] op_sel_hi:[1,1]
	v_pk_mul_f32 v[20:21], v[96:97], v[118:119] op_sel:[0,1] op_sel_hi:[1,1]
	v_add_f32_dpp v12, v12, v12 quad_perm:[1,0,3,2] row_mask:0xf bank_mask:0xf bound_ctrl:1
	v_add_f32_dpp v13, v13, v13 quad_perm:[1,0,3,2] row_mask:0xf bank_mask:0xf bound_ctrl:1
	v_pk_fma_f32 v[18:19], v[2:3], v[86:87], v[18:19]
	v_add_f32_dpp v12, v12, v12 quad_perm:[2,3,0,1] row_mask:0xf bank_mask:0xf bound_ctrl:1
	v_add_f32_dpp v13, v13, v13 quad_perm:[2,3,0,1] row_mask:0xf bank_mask:0xf bound_ctrl:1
	v_pk_fma_f32 v[20:21], v[4:5], v[88:89], v[20:21]
	v_add_f32_dpp v12, v12, v12 row_half_mirror row_mask:0xf bank_mask:0xf bound_ctrl:1
	v_add_f32_dpp v13, v13, v13 row_half_mirror row_mask:0xf bank_mask:0xf bound_ctrl:1
	s_nop 0
	s_nop 0
	v_add_f32_dpp v12, v12, v12 row_mirror row_mask:0xf bank_mask:0xf bound_ctrl:1
	v_add_f32_dpp v13, v13, v13 row_mirror row_mask:0xf bank_mask:0xf bound_ctrl:1
	v_pk_fma_f32 v[2:3], v[90:91], v[12:13], v[18:19] op_sel_hi:[1,0,1]
	v_pk_fma_f32 v[4:5], v[92:93], v[12:13], v[20:21] op_sel_hi:[1,0,1]
	v_fmac_f32_e64 v13, v121, v12
	ds_write2_b32 v9, v11, v13 offset0:64 offset1:80
	ds_read_b128 v[58:61], v6 offset:10240
	ds_read_b128 v[62:65], v6 offset:10256
	ds_read_b128 v[66:69], v6 offset:10272
	ds_read_b128 v[70:73], v6 offset:10288
	ds_read_b128 v[74:77], v6 offset:10304
	ds_read2st64_b32 v[118:119], v7 offset0:8 offset1:9
	ds_read_b64 v[120:121], v8 offset:32
	s_waitcnt lgkmcnt(13)
	s_nop 0
	v_pk_mul_f32 v[14:15], v[2:3], v[98:99] op_sel_hi:[0,1]
	v_pk_fma_f32 v[14:15], v[2:3], v[100:101], v[14:15] op_sel:[1,0,0] op_sel_hi:[1,1,1]
	v_pk_fma_f32 v[14:15], v[4:5], v[102:103], v[14:15] op_sel_hi:[0,1,1]
	v_pk_fma_f32 v[14:15], v[4:5], v[104:105], v[14:15] op_sel:[1,0,0] op_sel_hi:[1,1,1]
	v_pk_mul_f32 v[18:19], v[114:115], v[206:207] op_sel_hi:[1,0]
	v_pk_mul_f32 v[20:21], v[116:117], v[206:207] op_sel_hi:[1,0]
	v_add_f32_dpp v14, v14, v14 quad_perm:[1,0,3,2] row_mask:0xf bank_mask:0xf bound_ctrl:1
	v_add_f32_dpp v15, v15, v15 quad_perm:[1,0,3,2] row_mask:0xf bank_mask:0xf bound_ctrl:1
	v_pk_fma_f32 v[18:19], v[2:3], v[106:107], v[18:19]
	v_add_f32_dpp v14, v14, v14 quad_perm:[2,3,0,1] row_mask:0xf bank_mask:0xf bound_ctrl:1
	v_add_f32_dpp v15, v15, v15 quad_perm:[2,3,0,1] row_mask:0xf bank_mask:0xf bound_ctrl:1
	v_pk_fma_f32 v[20:21], v[4:5], v[108:109], v[20:21]
	v_add_f32_dpp v14, v14, v14 row_half_mirror row_mask:0xf bank_mask:0xf bound_ctrl:1
	v_add_f32_dpp v15, v15, v15 row_half_mirror row_mask:0xf bank_mask:0xf bound_ctrl:1
	s_nop 0
	s_nop 0
	v_add_f32_dpp v14, v14, v14 row_mirror row_mask:0xf bank_mask:0xf bound_ctrl:1
	v_add_f32_dpp v15, v15, v15 row_mirror row_mask:0xf bank_mask:0xf bound_ctrl:1
	v_pk_fma_f32 v[2:3], v[110:111], v[14:15], v[18:19] op_sel_hi:[1,0,1]
	v_pk_fma_f32 v[4:5], v[112:113], v[14:15], v[20:21] op_sel_hi:[1,0,1]
	v_fmac_f32_e64 v15, v208, v14
	ds_read_b128 v[78:81], v6 offset:11520
	ds_read_b128 v[82:85], v6 offset:11536
	ds_read_b128 v[86:89], v6 offset:11552
	ds_read_b128 v[90:93], v6 offset:11568
	ds_read_b128 v[94:97], v6 offset:11584
	s_waitcnt lgkmcnt(13)
	s_nop 0
	v_pk_mul_f32 v[16:17], v[2:3], v[186:187] op_sel_hi:[0,1]
	v_pk_fma_f32 v[16:17], v[2:3], v[188:189], v[16:17] op_sel:[1,0,0] op_sel_hi:[1,1,1]
	v_pk_fma_f32 v[16:17], v[4:5], v[190:191], v[16:17] op_sel_hi:[0,1,1]
	v_pk_fma_f32 v[16:17], v[4:5], v[192:193], v[16:17] op_sel:[1,0,0] op_sel_hi:[1,1,1]
	v_pk_mul_f32 v[18:19], v[202:203], v[206:207] op_sel:[0,1] op_sel_hi:[1,1]
	v_pk_mul_f32 v[20:21], v[204:205], v[206:207] op_sel:[0,1] op_sel_hi:[1,1]
	v_add_f32_dpp v16, v16, v16 quad_perm:[1,0,3,2] row_mask:0xf bank_mask:0xf bound_ctrl:1
	v_add_f32_dpp v17, v17, v17 quad_perm:[1,0,3,2] row_mask:0xf bank_mask:0xf bound_ctrl:1
	v_pk_fma_f32 v[18:19], v[2:3], v[194:195], v[18:19]
	v_add_f32_dpp v16, v16, v16 quad_perm:[2,3,0,1] row_mask:0xf bank_mask:0xf bound_ctrl:1
	v_add_f32_dpp v17, v17, v17 quad_perm:[2,3,0,1] row_mask:0xf bank_mask:0xf bound_ctrl:1
	v_pk_fma_f32 v[20:21], v[4:5], v[196:197], v[20:21]
	v_add_f32_dpp v16, v16, v16 row_half_mirror row_mask:0xf bank_mask:0xf bound_ctrl:1
	v_add_f32_dpp v17, v17, v17 row_half_mirror row_mask:0xf bank_mask:0xf bound_ctrl:1
	s_nop 0
	s_nop 0
	v_add_f32_dpp v16, v16, v16 row_mirror row_mask:0xf bank_mask:0xf bound_ctrl:1
	v_add_f32_dpp v17, v17, v17 row_mirror row_mask:0xf bank_mask:0xf bound_ctrl:1
	v_pk_fma_f32 v[2:3], v[198:199], v[16:17], v[18:19] op_sel_hi:[1,0,1]
	v_pk_fma_f32 v[4:5], v[200:201], v[16:17], v[20:21] op_sel_hi:[1,0,1]
	v_fmac_f32_e64 v17, v209, v16
	ds_write2_b32 v9, v15, v17 offset0:96 offset1:112
	ds_read_b128 v[98:101], v6 offset:12800
	ds_read_b128 v[102:105], v6 offset:12816
	ds_read_b128 v[106:109], v6 offset:12832
	ds_read_b128 v[110:113], v6 offset:12848
	ds_read_b128 v[114:117], v6 offset:12864
	ds_read2st64_b32 v[206:207], v7 offset0:10 offset1:11
	ds_read_b64 v[208:209], v8 offset:40
	s_waitcnt lgkmcnt(13)
	s_nop 0
	v_pk_mul_f32 v[10:11], v[2:3], v[58:59] op_sel_hi:[0,1]
	v_pk_fma_f32 v[10:11], v[2:3], v[60:61], v[10:11] op_sel:[1,0,0] op_sel_hi:[1,1,1]
	v_pk_fma_f32 v[10:11], v[4:5], v[62:63], v[10:11] op_sel_hi:[0,1,1]
	v_pk_fma_f32 v[10:11], v[4:5], v[64:65], v[10:11] op_sel:[1,0,0] op_sel_hi:[1,1,1]
	v_pk_mul_f32 v[18:19], v[74:75], v[118:119] op_sel_hi:[1,0]
	v_pk_mul_f32 v[20:21], v[76:77], v[118:119] op_sel_hi:[1,0]
	v_add_f32_dpp v10, v10, v10 quad_perm:[1,0,3,2] row_mask:0xf bank_mask:0xf bound_ctrl:1
	v_add_f32_dpp v11, v11, v11 quad_perm:[1,0,3,2] row_mask:0xf bank_mask:0xf bound_ctrl:1
	v_pk_fma_f32 v[18:19], v[2:3], v[66:67], v[18:19]
	v_add_f32_dpp v10, v10, v10 quad_perm:[2,3,0,1] row_mask:0xf bank_mask:0xf bound_ctrl:1
	v_add_f32_dpp v11, v11, v11 quad_perm:[2,3,0,1] row_mask:0xf bank_mask:0xf bound_ctrl:1
	v_pk_fma_f32 v[20:21], v[4:5], v[68:69], v[20:21]
	v_add_f32_dpp v10, v10, v10 row_half_mirror row_mask:0xf bank_mask:0xf bound_ctrl:1
	v_add_f32_dpp v11, v11, v11 row_half_mirror row_mask:0xf bank_mask:0xf bound_ctrl:1
	s_nop 0
	s_nop 0
	v_add_f32_dpp v10, v10, v10 row_mirror row_mask:0xf bank_mask:0xf bound_ctrl:1
	v_add_f32_dpp v11, v11, v11 row_mirror row_mask:0xf bank_mask:0xf bound_ctrl:1
	v_pk_fma_f32 v[2:3], v[70:71], v[10:11], v[18:19] op_sel_hi:[1,0,1]
	v_pk_fma_f32 v[4:5], v[72:73], v[10:11], v[20:21] op_sel_hi:[1,0,1]
	v_fmac_f32_e64 v11, v120, v10
	ds_read_b128 v[186:189], v6 offset:14080
	ds_read_b128 v[190:193], v6 offset:14096
	ds_read_b128 v[194:197], v6 offset:14112
	ds_read_b128 v[198:201], v6 offset:14128
	ds_read_b128 v[202:205], v6 offset:14144
	s_waitcnt lgkmcnt(13)
	s_nop 0
	v_pk_mul_f32 v[12:13], v[2:3], v[78:79] op_sel_hi:[0,1]
	v_pk_fma_f32 v[12:13], v[2:3], v[80:81], v[12:13] op_sel:[1,0,0] op_sel_hi:[1,1,1]
	v_pk_fma_f32 v[12:13], v[4:5], v[82:83], v[12:13] op_sel_hi:[0,1,1]
	v_pk_fma_f32 v[12:13], v[4:5], v[84:85], v[12:13] op_sel:[1,0,0] op_sel_hi:[1,1,1]
	v_pk_mul_f32 v[18:19], v[94:95], v[118:119] op_sel:[0,1] op_sel_hi:[1,1]
	v_pk_mul_f32 v[20:21], v[96:97], v[118:119] op_sel:[0,1] op_sel_hi:[1,1]
	v_add_f32_dpp v12, v12, v12 quad_perm:[1,0,3,2] row_mask:0xf bank_mask:0xf bound_ctrl:1
	v_add_f32_dpp v13, v13, v13 quad_perm:[1,0,3,2] row_mask:0xf bank_mask:0xf bound_ctrl:1
	v_pk_fma_f32 v[18:19], v[2:3], v[86:87], v[18:19]
	v_add_f32_dpp v12, v12, v12 quad_perm:[2,3,0,1] row_mask:0xf bank_mask:0xf bound_ctrl:1
	v_add_f32_dpp v13, v13, v13 quad_perm:[2,3,0,1] row_mask:0xf bank_mask:0xf bound_ctrl:1
	v_pk_fma_f32 v[20:21], v[4:5], v[88:89], v[20:21]
	v_add_f32_dpp v12, v12, v12 row_half_mirror row_mask:0xf bank_mask:0xf bound_ctrl:1
	v_add_f32_dpp v13, v13, v13 row_half_mirror row_mask:0xf bank_mask:0xf bound_ctrl:1
	s_nop 0
	s_nop 0
	v_add_f32_dpp v12, v12, v12 row_mirror row_mask:0xf bank_mask:0xf bound_ctrl:1
	v_add_f32_dpp v13, v13, v13 row_mirror row_mask:0xf bank_mask:0xf bound_ctrl:1
	v_pk_fma_f32 v[2:3], v[90:91], v[12:13], v[18:19] op_sel_hi:[1,0,1]
	v_pk_fma_f32 v[4:5], v[92:93], v[12:13], v[20:21] op_sel_hi:[1,0,1]
	v_fmac_f32_e64 v13, v121, v12
	ds_write2_b32 v9, v11, v13 offset0:128 offset1:144
	ds_read_b128 v[58:61], v6 offset:15360
	ds_read_b128 v[62:65], v6 offset:15376
	ds_read_b128 v[66:69], v6 offset:15392
	ds_read_b128 v[70:73], v6 offset:15408
	ds_read_b128 v[74:77], v6 offset:15424
	ds_read2st64_b32 v[118:119], v7 offset0:12 offset1:13
	ds_read_b64 v[120:121], v8 offset:48
	s_waitcnt lgkmcnt(13)
	s_nop 0
	v_pk_mul_f32 v[14:15], v[2:3], v[98:99] op_sel_hi:[0,1]
	v_pk_fma_f32 v[14:15], v[2:3], v[100:101], v[14:15] op_sel:[1,0,0] op_sel_hi:[1,1,1]
	v_pk_fma_f32 v[14:15], v[4:5], v[102:103], v[14:15] op_sel_hi:[0,1,1]
	v_pk_fma_f32 v[14:15], v[4:5], v[104:105], v[14:15] op_sel:[1,0,0] op_sel_hi:[1,1,1]
	v_pk_mul_f32 v[18:19], v[114:115], v[206:207] op_sel_hi:[1,0]
	v_pk_mul_f32 v[20:21], v[116:117], v[206:207] op_sel_hi:[1,0]
	v_add_f32_dpp v14, v14, v14 quad_perm:[1,0,3,2] row_mask:0xf bank_mask:0xf bound_ctrl:1
	v_add_f32_dpp v15, v15, v15 quad_perm:[1,0,3,2] row_mask:0xf bank_mask:0xf bound_ctrl:1
	v_pk_fma_f32 v[18:19], v[2:3], v[106:107], v[18:19]
	v_add_f32_dpp v14, v14, v14 quad_perm:[2,3,0,1] row_mask:0xf bank_mask:0xf bound_ctrl:1
	v_add_f32_dpp v15, v15, v15 quad_perm:[2,3,0,1] row_mask:0xf bank_mask:0xf bound_ctrl:1
	v_pk_fma_f32 v[20:21], v[4:5], v[108:109], v[20:21]
	v_add_f32_dpp v14, v14, v14 row_half_mirror row_mask:0xf bank_mask:0xf bound_ctrl:1
	v_add_f32_dpp v15, v15, v15 row_half_mirror row_mask:0xf bank_mask:0xf bound_ctrl:1
	s_nop 0
	s_nop 0
	v_add_f32_dpp v14, v14, v14 row_mirror row_mask:0xf bank_mask:0xf bound_ctrl:1
	v_add_f32_dpp v15, v15, v15 row_mirror row_mask:0xf bank_mask:0xf bound_ctrl:1
	v_pk_fma_f32 v[2:3], v[110:111], v[14:15], v[18:19] op_sel_hi:[1,0,1]
	v_pk_fma_f32 v[4:5], v[112:113], v[14:15], v[20:21] op_sel_hi:[1,0,1]
	v_fmac_f32_e64 v15, v208, v14
	ds_read_b128 v[78:81], v6 offset:16640
	ds_read_b128 v[82:85], v6 offset:16656
	ds_read_b128 v[86:89], v6 offset:16672
	ds_read_b128 v[90:93], v6 offset:16688
	ds_read_b128 v[94:97], v6 offset:16704
	s_waitcnt lgkmcnt(13)
	s_nop 0
	v_pk_mul_f32 v[16:17], v[2:3], v[186:187] op_sel_hi:[0,1]
	v_pk_fma_f32 v[16:17], v[2:3], v[188:189], v[16:17] op_sel:[1,0,0] op_sel_hi:[1,1,1]
	v_pk_fma_f32 v[16:17], v[4:5], v[190:191], v[16:17] op_sel_hi:[0,1,1]
	v_pk_fma_f32 v[16:17], v[4:5], v[192:193], v[16:17] op_sel:[1,0,0] op_sel_hi:[1,1,1]
	v_pk_mul_f32 v[18:19], v[202:203], v[206:207] op_sel:[0,1] op_sel_hi:[1,1]
	v_pk_mul_f32 v[20:21], v[204:205], v[206:207] op_sel:[0,1] op_sel_hi:[1,1]
	v_add_f32_dpp v16, v16, v16 quad_perm:[1,0,3,2] row_mask:0xf bank_mask:0xf bound_ctrl:1
	v_add_f32_dpp v17, v17, v17 quad_perm:[1,0,3,2] row_mask:0xf bank_mask:0xf bound_ctrl:1
	v_pk_fma_f32 v[18:19], v[2:3], v[194:195], v[18:19]
	v_add_f32_dpp v16, v16, v16 quad_perm:[2,3,0,1] row_mask:0xf bank_mask:0xf bound_ctrl:1
	v_add_f32_dpp v17, v17, v17 quad_perm:[2,3,0,1] row_mask:0xf bank_mask:0xf bound_ctrl:1
	v_pk_fma_f32 v[20:21], v[4:5], v[196:197], v[20:21]
	v_add_f32_dpp v16, v16, v16 row_half_mirror row_mask:0xf bank_mask:0xf bound_ctrl:1
	v_add_f32_dpp v17, v17, v17 row_half_mirror row_mask:0xf bank_mask:0xf bound_ctrl:1
	s_nop 0
	s_nop 0
	v_add_f32_dpp v16, v16, v16 row_mirror row_mask:0xf bank_mask:0xf bound_ctrl:1
	v_add_f32_dpp v17, v17, v17 row_mirror row_mask:0xf bank_mask:0xf bound_ctrl:1
	v_pk_fma_f32 v[2:3], v[198:199], v[16:17], v[18:19] op_sel_hi:[1,0,1]
	v_pk_fma_f32 v[4:5], v[200:201], v[16:17], v[20:21] op_sel_hi:[1,0,1]
	v_fmac_f32_e64 v17, v209, v16
	ds_write2_b32 v9, v15, v17 offset0:160 offset1:176
	ds_read_b128 v[98:101], v6 offset:17920
	ds_read_b128 v[102:105], v6 offset:17936
	ds_read_b128 v[106:109], v6 offset:17952
	ds_read_b128 v[110:113], v6 offset:17968
	ds_read_b128 v[114:117], v6 offset:17984
	ds_read2st64_b32 v[206:207], v7 offset0:14 offset1:15
	ds_read_b64 v[208:209], v8 offset:56
	s_waitcnt lgkmcnt(13)
	s_nop 0
	v_pk_mul_f32 v[10:11], v[2:3], v[58:59] op_sel_hi:[0,1]
	v_pk_fma_f32 v[10:11], v[2:3], v[60:61], v[10:11] op_sel:[1,0,0] op_sel_hi:[1,1,1]
	v_pk_fma_f32 v[10:11], v[4:5], v[62:63], v[10:11] op_sel_hi:[0,1,1]
	v_pk_fma_f32 v[10:11], v[4:5], v[64:65], v[10:11] op_sel:[1,0,0] op_sel_hi:[1,1,1]
	v_pk_mul_f32 v[18:19], v[74:75], v[118:119] op_sel_hi:[1,0]
	v_pk_mul_f32 v[20:21], v[76:77], v[118:119] op_sel_hi:[1,0]
	v_add_f32_dpp v10, v10, v10 quad_perm:[1,0,3,2] row_mask:0xf bank_mask:0xf bound_ctrl:1
	v_add_f32_dpp v11, v11, v11 quad_perm:[1,0,3,2] row_mask:0xf bank_mask:0xf bound_ctrl:1
	v_pk_fma_f32 v[18:19], v[2:3], v[66:67], v[18:19]
	v_add_f32_dpp v10, v10, v10 quad_perm:[2,3,0,1] row_mask:0xf bank_mask:0xf bound_ctrl:1
	v_add_f32_dpp v11, v11, v11 quad_perm:[2,3,0,1] row_mask:0xf bank_mask:0xf bound_ctrl:1
	v_pk_fma_f32 v[20:21], v[4:5], v[68:69], v[20:21]
	v_add_f32_dpp v10, v10, v10 row_half_mirror row_mask:0xf bank_mask:0xf bound_ctrl:1
	v_add_f32_dpp v11, v11, v11 row_half_mirror row_mask:0xf bank_mask:0xf bound_ctrl:1
	s_nop 0
	s_nop 0
	v_add_f32_dpp v10, v10, v10 row_mirror row_mask:0xf bank_mask:0xf bound_ctrl:1
	v_add_f32_dpp v11, v11, v11 row_mirror row_mask:0xf bank_mask:0xf bound_ctrl:1
	v_pk_fma_f32 v[2:3], v[70:71], v[10:11], v[18:19] op_sel_hi:[1,0,1]
	v_pk_fma_f32 v[4:5], v[72:73], v[10:11], v[20:21] op_sel_hi:[1,0,1]
	v_fmac_f32_e64 v11, v120, v10
	ds_read_b128 v[186:189], v6 offset:19200
	ds_read_b128 v[190:193], v6 offset:19216
	ds_read_b128 v[194:197], v6 offset:19232
	ds_read_b128 v[198:201], v6 offset:19248
	ds_read_b128 v[202:205], v6 offset:19264
	s_waitcnt lgkmcnt(13)
	s_nop 0
	v_pk_mul_f32 v[12:13], v[2:3], v[78:79] op_sel_hi:[0,1]
	v_pk_fma_f32 v[12:13], v[2:3], v[80:81], v[12:13] op_sel:[1,0,0] op_sel_hi:[1,1,1]
	v_pk_fma_f32 v[12:13], v[4:5], v[82:83], v[12:13] op_sel_hi:[0,1,1]
	v_pk_fma_f32 v[12:13], v[4:5], v[84:85], v[12:13] op_sel:[1,0,0] op_sel_hi:[1,1,1]
	v_pk_mul_f32 v[18:19], v[94:95], v[118:119] op_sel:[0,1] op_sel_hi:[1,1]
	v_pk_mul_f32 v[20:21], v[96:97], v[118:119] op_sel:[0,1] op_sel_hi:[1,1]
	v_add_f32_dpp v12, v12, v12 quad_perm:[1,0,3,2] row_mask:0xf bank_mask:0xf bound_ctrl:1
	v_add_f32_dpp v13, v13, v13 quad_perm:[1,0,3,2] row_mask:0xf bank_mask:0xf bound_ctrl:1
	v_pk_fma_f32 v[18:19], v[2:3], v[86:87], v[18:19]
	v_add_f32_dpp v12, v12, v12 quad_perm:[2,3,0,1] row_mask:0xf bank_mask:0xf bound_ctrl:1
	v_add_f32_dpp v13, v13, v13 quad_perm:[2,3,0,1] row_mask:0xf bank_mask:0xf bound_ctrl:1
	v_pk_fma_f32 v[20:21], v[4:5], v[88:89], v[20:21]
	v_add_f32_dpp v12, v12, v12 row_half_mirror row_mask:0xf bank_mask:0xf bound_ctrl:1
	v_add_f32_dpp v13, v13, v13 row_half_mirror row_mask:0xf bank_mask:0xf bound_ctrl:1
	s_nop 0
	s_nop 0
	v_add_f32_dpp v12, v12, v12 row_mirror row_mask:0xf bank_mask:0xf bound_ctrl:1
	v_add_f32_dpp v13, v13, v13 row_mirror row_mask:0xf bank_mask:0xf bound_ctrl:1
	v_pk_fma_f32 v[2:3], v[90:91], v[12:13], v[18:19] op_sel_hi:[1,0,1]
	v_pk_fma_f32 v[4:5], v[92:93], v[12:13], v[20:21] op_sel_hi:[1,0,1]
	v_fmac_f32_e64 v13, v121, v12
	ds_write2_b32 v9, v11, v13 offset0:192 offset1:208
	ds_read_b128 v[58:61], v6 offset:20480
	ds_read_b128 v[62:65], v6 offset:20496
	ds_read_b128 v[66:69], v6 offset:20512
	ds_read_b128 v[70:73], v6 offset:20528
	ds_read_b128 v[74:77], v6 offset:20544
	ds_read2st64_b32 v[118:119], v7 offset0:16 offset1:17
	ds_read_b64 v[120:121], v8 offset:64
	s_waitcnt lgkmcnt(13)
	s_nop 0
	v_pk_mul_f32 v[14:15], v[2:3], v[98:99] op_sel_hi:[0,1]
	v_pk_fma_f32 v[14:15], v[2:3], v[100:101], v[14:15] op_sel:[1,0,0] op_sel_hi:[1,1,1]
	v_pk_fma_f32 v[14:15], v[4:5], v[102:103], v[14:15] op_sel_hi:[0,1,1]
	v_pk_fma_f32 v[14:15], v[4:5], v[104:105], v[14:15] op_sel:[1,0,0] op_sel_hi:[1,1,1]
	v_pk_mul_f32 v[18:19], v[114:115], v[206:207] op_sel_hi:[1,0]
	v_pk_mul_f32 v[20:21], v[116:117], v[206:207] op_sel_hi:[1,0]
	v_add_f32_dpp v14, v14, v14 quad_perm:[1,0,3,2] row_mask:0xf bank_mask:0xf bound_ctrl:1
	v_add_f32_dpp v15, v15, v15 quad_perm:[1,0,3,2] row_mask:0xf bank_mask:0xf bound_ctrl:1
	v_pk_fma_f32 v[18:19], v[2:3], v[106:107], v[18:19]
	v_add_f32_dpp v14, v14, v14 quad_perm:[2,3,0,1] row_mask:0xf bank_mask:0xf bound_ctrl:1
	v_add_f32_dpp v15, v15, v15 quad_perm:[2,3,0,1] row_mask:0xf bank_mask:0xf bound_ctrl:1
	v_pk_fma_f32 v[20:21], v[4:5], v[108:109], v[20:21]
	v_add_f32_dpp v14, v14, v14 row_half_mirror row_mask:0xf bank_mask:0xf bound_ctrl:1
	v_add_f32_dpp v15, v15, v15 row_half_mirror row_mask:0xf bank_mask:0xf bound_ctrl:1
	s_nop 0
	s_nop 0
	v_add_f32_dpp v14, v14, v14 row_mirror row_mask:0xf bank_mask:0xf bound_ctrl:1
	v_add_f32_dpp v15, v15, v15 row_mirror row_mask:0xf bank_mask:0xf bound_ctrl:1
	v_pk_fma_f32 v[2:3], v[110:111], v[14:15], v[18:19] op_sel_hi:[1,0,1]
	v_pk_fma_f32 v[4:5], v[112:113], v[14:15], v[20:21] op_sel_hi:[1,0,1]
	v_fmac_f32_e64 v15, v208, v14
	ds_read_b128 v[78:81], v6 offset:21760
	ds_read_b128 v[82:85], v6 offset:21776
	ds_read_b128 v[86:89], v6 offset:21792
	ds_read_b128 v[90:93], v6 offset:21808
	ds_read_b128 v[94:97], v6 offset:21824
	s_waitcnt lgkmcnt(13)
	s_nop 0
	v_pk_mul_f32 v[16:17], v[2:3], v[186:187] op_sel_hi:[0,1]
	v_pk_fma_f32 v[16:17], v[2:3], v[188:189], v[16:17] op_sel:[1,0,0] op_sel_hi:[1,1,1]
	v_pk_fma_f32 v[16:17], v[4:5], v[190:191], v[16:17] op_sel_hi:[0,1,1]
	v_pk_fma_f32 v[16:17], v[4:5], v[192:193], v[16:17] op_sel:[1,0,0] op_sel_hi:[1,1,1]
	v_pk_mul_f32 v[18:19], v[202:203], v[206:207] op_sel:[0,1] op_sel_hi:[1,1]
	v_pk_mul_f32 v[20:21], v[204:205], v[206:207] op_sel:[0,1] op_sel_hi:[1,1]
	v_add_f32_dpp v16, v16, v16 quad_perm:[1,0,3,2] row_mask:0xf bank_mask:0xf bound_ctrl:1
	v_add_f32_dpp v17, v17, v17 quad_perm:[1,0,3,2] row_mask:0xf bank_mask:0xf bound_ctrl:1
	v_pk_fma_f32 v[18:19], v[2:3], v[194:195], v[18:19]
	v_add_f32_dpp v16, v16, v16 quad_perm:[2,3,0,1] row_mask:0xf bank_mask:0xf bound_ctrl:1
	v_add_f32_dpp v17, v17, v17 quad_perm:[2,3,0,1] row_mask:0xf bank_mask:0xf bound_ctrl:1
	v_pk_fma_f32 v[20:21], v[4:5], v[196:197], v[20:21]
	v_add_f32_dpp v16, v16, v16 row_half_mirror row_mask:0xf bank_mask:0xf bound_ctrl:1
	v_add_f32_dpp v17, v17, v17 row_half_mirror row_mask:0xf bank_mask:0xf bound_ctrl:1
	s_nop 0
	s_nop 0
	v_add_f32_dpp v16, v16, v16 row_mirror row_mask:0xf bank_mask:0xf bound_ctrl:1
	v_add_f32_dpp v17, v17, v17 row_mirror row_mask:0xf bank_mask:0xf bound_ctrl:1
	v_pk_fma_f32 v[2:3], v[198:199], v[16:17], v[18:19] op_sel_hi:[1,0,1]
	v_pk_fma_f32 v[4:5], v[200:201], v[16:17], v[20:21] op_sel_hi:[1,0,1]
	v_fmac_f32_e64 v17, v209, v16
	ds_write2_b32 v9, v15, v17 offset0:224 offset1:240
	ds_read_b128 v[98:101], v6 offset:23040
	ds_read_b128 v[102:105], v6 offset:23056
	ds_read_b128 v[106:109], v6 offset:23072
	ds_read_b128 v[110:113], v6 offset:23088
	ds_read_b128 v[114:117], v6 offset:23104
	ds_read2st64_b32 v[206:207], v7 offset0:18 offset1:19
	ds_read_b64 v[208:209], v8 offset:72
	s_waitcnt lgkmcnt(13)
	s_nop 0
	v_pk_mul_f32 v[10:11], v[2:3], v[58:59] op_sel_hi:[0,1]
	v_pk_fma_f32 v[10:11], v[2:3], v[60:61], v[10:11] op_sel:[1,0,0] op_sel_hi:[1,1,1]
	v_pk_fma_f32 v[10:11], v[4:5], v[62:63], v[10:11] op_sel_hi:[0,1,1]
	v_pk_fma_f32 v[10:11], v[4:5], v[64:65], v[10:11] op_sel:[1,0,0] op_sel_hi:[1,1,1]
	v_pk_mul_f32 v[18:19], v[74:75], v[118:119] op_sel_hi:[1,0]
	v_pk_mul_f32 v[20:21], v[76:77], v[118:119] op_sel_hi:[1,0]
	v_add_f32_dpp v10, v10, v10 quad_perm:[1,0,3,2] row_mask:0xf bank_mask:0xf bound_ctrl:1
	v_add_f32_dpp v11, v11, v11 quad_perm:[1,0,3,2] row_mask:0xf bank_mask:0xf bound_ctrl:1
	v_pk_fma_f32 v[18:19], v[2:3], v[66:67], v[18:19]
	v_add_f32_dpp v10, v10, v10 quad_perm:[2,3,0,1] row_mask:0xf bank_mask:0xf bound_ctrl:1
	v_add_f32_dpp v11, v11, v11 quad_perm:[2,3,0,1] row_mask:0xf bank_mask:0xf bound_ctrl:1
	v_pk_fma_f32 v[20:21], v[4:5], v[68:69], v[20:21]
	v_add_f32_dpp v10, v10, v10 row_half_mirror row_mask:0xf bank_mask:0xf bound_ctrl:1
	v_add_f32_dpp v11, v11, v11 row_half_mirror row_mask:0xf bank_mask:0xf bound_ctrl:1
	s_nop 0
	s_nop 0
	v_add_f32_dpp v10, v10, v10 row_mirror row_mask:0xf bank_mask:0xf bound_ctrl:1
	v_add_f32_dpp v11, v11, v11 row_mirror row_mask:0xf bank_mask:0xf bound_ctrl:1
	v_pk_fma_f32 v[2:3], v[70:71], v[10:11], v[18:19] op_sel_hi:[1,0,1]
	v_pk_fma_f32 v[4:5], v[72:73], v[10:11], v[20:21] op_sel_hi:[1,0,1]
	v_fmac_f32_e64 v11, v120, v10
	ds_read_b128 v[186:189], v6 offset:24320
	ds_read_b128 v[190:193], v6 offset:24336
	ds_read_b128 v[194:197], v6 offset:24352
	ds_read_b128 v[198:201], v6 offset:24368
	ds_read_b128 v[202:205], v6 offset:24384
	s_waitcnt lgkmcnt(13)
	s_nop 0
	v_pk_mul_f32 v[12:13], v[2:3], v[78:79] op_sel_hi:[0,1]
	v_pk_fma_f32 v[12:13], v[2:3], v[80:81], v[12:13] op_sel:[1,0,0] op_sel_hi:[1,1,1]
	v_pk_fma_f32 v[12:13], v[4:5], v[82:83], v[12:13] op_sel_hi:[0,1,1]
	v_pk_fma_f32 v[12:13], v[4:5], v[84:85], v[12:13] op_sel:[1,0,0] op_sel_hi:[1,1,1]
	v_pk_mul_f32 v[18:19], v[94:95], v[118:119] op_sel:[0,1] op_sel_hi:[1,1]
	v_pk_mul_f32 v[20:21], v[96:97], v[118:119] op_sel:[0,1] op_sel_hi:[1,1]
	v_add_f32_dpp v12, v12, v12 quad_perm:[1,0,3,2] row_mask:0xf bank_mask:0xf bound_ctrl:1
	v_add_f32_dpp v13, v13, v13 quad_perm:[1,0,3,2] row_mask:0xf bank_mask:0xf bound_ctrl:1
	v_pk_fma_f32 v[18:19], v[2:3], v[86:87], v[18:19]
	v_add_f32_dpp v12, v12, v12 quad_perm:[2,3,0,1] row_mask:0xf bank_mask:0xf bound_ctrl:1
	v_add_f32_dpp v13, v13, v13 quad_perm:[2,3,0,1] row_mask:0xf bank_mask:0xf bound_ctrl:1
	v_pk_fma_f32 v[20:21], v[4:5], v[88:89], v[20:21]
	v_add_f32_dpp v12, v12, v12 row_half_mirror row_mask:0xf bank_mask:0xf bound_ctrl:1
	v_add_f32_dpp v13, v13, v13 row_half_mirror row_mask:0xf bank_mask:0xf bound_ctrl:1
	s_nop 0
	s_nop 0
	v_add_f32_dpp v12, v12, v12 row_mirror row_mask:0xf bank_mask:0xf bound_ctrl:1
	v_add_f32_dpp v13, v13, v13 row_mirror row_mask:0xf bank_mask:0xf bound_ctrl:1
	v_pk_fma_f32 v[2:3], v[90:91], v[12:13], v[18:19] op_sel_hi:[1,0,1]
	v_pk_fma_f32 v[4:5], v[92:93], v[12:13], v[20:21] op_sel_hi:[1,0,1]
	v_fmac_f32_e64 v13, v121, v12
	ds_write2_b32 v22, v11, v13 offset1:16
	ds_read_b128 v[58:61], v6 offset:25600
	ds_read_b128 v[62:65], v6 offset:25616
	ds_read_b128 v[66:69], v6 offset:25632
	ds_read_b128 v[70:73], v6 offset:25648
	ds_read_b128 v[74:77], v6 offset:25664
	ds_read2st64_b32 v[118:119], v7 offset0:20 offset1:21
	ds_read_b64 v[120:121], v8 offset:80
	s_waitcnt lgkmcnt(13)
	s_nop 0
	v_pk_mul_f32 v[14:15], v[2:3], v[98:99] op_sel_hi:[0,1]
	v_pk_fma_f32 v[14:15], v[2:3], v[100:101], v[14:15] op_sel:[1,0,0] op_sel_hi:[1,1,1]
	v_pk_fma_f32 v[14:15], v[4:5], v[102:103], v[14:15] op_sel_hi:[0,1,1]
	v_pk_fma_f32 v[14:15], v[4:5], v[104:105], v[14:15] op_sel:[1,0,0] op_sel_hi:[1,1,1]
	v_pk_mul_f32 v[18:19], v[114:115], v[206:207] op_sel_hi:[1,0]
	v_pk_mul_f32 v[20:21], v[116:117], v[206:207] op_sel_hi:[1,0]
	v_add_f32_dpp v14, v14, v14 quad_perm:[1,0,3,2] row_mask:0xf bank_mask:0xf bound_ctrl:1
	v_add_f32_dpp v15, v15, v15 quad_perm:[1,0,3,2] row_mask:0xf bank_mask:0xf bound_ctrl:1
	v_pk_fma_f32 v[18:19], v[2:3], v[106:107], v[18:19]
	v_add_f32_dpp v14, v14, v14 quad_perm:[2,3,0,1] row_mask:0xf bank_mask:0xf bound_ctrl:1
	v_add_f32_dpp v15, v15, v15 quad_perm:[2,3,0,1] row_mask:0xf bank_mask:0xf bound_ctrl:1
	v_pk_fma_f32 v[20:21], v[4:5], v[108:109], v[20:21]
	v_add_f32_dpp v14, v14, v14 row_half_mirror row_mask:0xf bank_mask:0xf bound_ctrl:1
	v_add_f32_dpp v15, v15, v15 row_half_mirror row_mask:0xf bank_mask:0xf bound_ctrl:1
	s_nop 0
	s_nop 0
	v_add_f32_dpp v14, v14, v14 row_mirror row_mask:0xf bank_mask:0xf bound_ctrl:1
	v_add_f32_dpp v15, v15, v15 row_mirror row_mask:0xf bank_mask:0xf bound_ctrl:1
	v_pk_fma_f32 v[2:3], v[110:111], v[14:15], v[18:19] op_sel_hi:[1,0,1]
	v_pk_fma_f32 v[4:5], v[112:113], v[14:15], v[20:21] op_sel_hi:[1,0,1]
	v_fmac_f32_e64 v15, v208, v14
	ds_read_b128 v[78:81], v6 offset:26880
	ds_read_b128 v[82:85], v6 offset:26896
	ds_read_b128 v[86:89], v6 offset:26912
	ds_read_b128 v[90:93], v6 offset:26928
	ds_read_b128 v[94:97], v6 offset:26944
	s_waitcnt lgkmcnt(13)
	s_nop 0
	v_pk_mul_f32 v[16:17], v[2:3], v[186:187] op_sel_hi:[0,1]
	v_pk_fma_f32 v[16:17], v[2:3], v[188:189], v[16:17] op_sel:[1,0,0] op_sel_hi:[1,1,1]
	v_pk_fma_f32 v[16:17], v[4:5], v[190:191], v[16:17] op_sel_hi:[0,1,1]
	v_pk_fma_f32 v[16:17], v[4:5], v[192:193], v[16:17] op_sel:[1,0,0] op_sel_hi:[1,1,1]
	v_pk_mul_f32 v[18:19], v[202:203], v[206:207] op_sel:[0,1] op_sel_hi:[1,1]
	v_pk_mul_f32 v[20:21], v[204:205], v[206:207] op_sel:[0,1] op_sel_hi:[1,1]
	v_add_f32_dpp v16, v16, v16 quad_perm:[1,0,3,2] row_mask:0xf bank_mask:0xf bound_ctrl:1
	v_add_f32_dpp v17, v17, v17 quad_perm:[1,0,3,2] row_mask:0xf bank_mask:0xf bound_ctrl:1
	v_pk_fma_f32 v[18:19], v[2:3], v[194:195], v[18:19]
	v_add_f32_dpp v16, v16, v16 quad_perm:[2,3,0,1] row_mask:0xf bank_mask:0xf bound_ctrl:1
	v_add_f32_dpp v17, v17, v17 quad_perm:[2,3,0,1] row_mask:0xf bank_mask:0xf bound_ctrl:1
	v_pk_fma_f32 v[20:21], v[4:5], v[196:197], v[20:21]
	v_add_f32_dpp v16, v16, v16 row_half_mirror row_mask:0xf bank_mask:0xf bound_ctrl:1
	v_add_f32_dpp v17, v17, v17 row_half_mirror row_mask:0xf bank_mask:0xf bound_ctrl:1
	s_nop 0
	s_nop 0
	v_add_f32_dpp v16, v16, v16 row_mirror row_mask:0xf bank_mask:0xf bound_ctrl:1
	v_add_f32_dpp v17, v17, v17 row_mirror row_mask:0xf bank_mask:0xf bound_ctrl:1
	v_pk_fma_f32 v[2:3], v[198:199], v[16:17], v[18:19] op_sel_hi:[1,0,1]
	v_pk_fma_f32 v[4:5], v[200:201], v[16:17], v[20:21] op_sel_hi:[1,0,1]
	v_fmac_f32_e64 v17, v209, v16
	ds_write2_b32 v22, v15, v17 offset0:32 offset1:48
	ds_read_b128 v[98:101], v6 offset:28160
	ds_read_b128 v[102:105], v6 offset:28176
	ds_read_b128 v[106:109], v6 offset:28192
	ds_read_b128 v[110:113], v6 offset:28208
	ds_read_b128 v[114:117], v6 offset:28224
	ds_read2st64_b32 v[206:207], v7 offset0:22 offset1:23
	ds_read_b64 v[208:209], v8 offset:88
	s_waitcnt lgkmcnt(13)
	s_nop 0
	v_pk_mul_f32 v[10:11], v[2:3], v[58:59] op_sel_hi:[0,1]
	v_pk_fma_f32 v[10:11], v[2:3], v[60:61], v[10:11] op_sel:[1,0,0] op_sel_hi:[1,1,1]
	v_pk_fma_f32 v[10:11], v[4:5], v[62:63], v[10:11] op_sel_hi:[0,1,1]
	v_pk_fma_f32 v[10:11], v[4:5], v[64:65], v[10:11] op_sel:[1,0,0] op_sel_hi:[1,1,1]
	v_pk_mul_f32 v[18:19], v[74:75], v[118:119] op_sel_hi:[1,0]
	v_pk_mul_f32 v[20:21], v[76:77], v[118:119] op_sel_hi:[1,0]
	v_add_f32_dpp v10, v10, v10 quad_perm:[1,0,3,2] row_mask:0xf bank_mask:0xf bound_ctrl:1
	v_add_f32_dpp v11, v11, v11 quad_perm:[1,0,3,2] row_mask:0xf bank_mask:0xf bound_ctrl:1
	v_pk_fma_f32 v[18:19], v[2:3], v[66:67], v[18:19]
	v_add_f32_dpp v10, v10, v10 quad_perm:[2,3,0,1] row_mask:0xf bank_mask:0xf bound_ctrl:1
	v_add_f32_dpp v11, v11, v11 quad_perm:[2,3,0,1] row_mask:0xf bank_mask:0xf bound_ctrl:1
	v_pk_fma_f32 v[20:21], v[4:5], v[68:69], v[20:21]
	v_add_f32_dpp v10, v10, v10 row_half_mirror row_mask:0xf bank_mask:0xf bound_ctrl:1
	v_add_f32_dpp v11, v11, v11 row_half_mirror row_mask:0xf bank_mask:0xf bound_ctrl:1
	s_nop 0
	s_nop 0
	v_add_f32_dpp v10, v10, v10 row_mirror row_mask:0xf bank_mask:0xf bound_ctrl:1
	v_add_f32_dpp v11, v11, v11 row_mirror row_mask:0xf bank_mask:0xf bound_ctrl:1
	v_pk_fma_f32 v[2:3], v[70:71], v[10:11], v[18:19] op_sel_hi:[1,0,1]
	v_pk_fma_f32 v[4:5], v[72:73], v[10:11], v[20:21] op_sel_hi:[1,0,1]
	v_fmac_f32_e64 v11, v120, v10
	ds_read_b128 v[186:189], v6 offset:29440
	ds_read_b128 v[190:193], v6 offset:29456
	ds_read_b128 v[194:197], v6 offset:29472
	ds_read_b128 v[198:201], v6 offset:29488
	ds_read_b128 v[202:205], v6 offset:29504
	s_waitcnt lgkmcnt(13)
	s_nop 0
	v_pk_mul_f32 v[12:13], v[2:3], v[78:79] op_sel_hi:[0,1]
	v_pk_fma_f32 v[12:13], v[2:3], v[80:81], v[12:13] op_sel:[1,0,0] op_sel_hi:[1,1,1]
	v_pk_fma_f32 v[12:13], v[4:5], v[82:83], v[12:13] op_sel_hi:[0,1,1]
	v_pk_fma_f32 v[12:13], v[4:5], v[84:85], v[12:13] op_sel:[1,0,0] op_sel_hi:[1,1,1]
	v_pk_mul_f32 v[18:19], v[94:95], v[118:119] op_sel:[0,1] op_sel_hi:[1,1]
	v_pk_mul_f32 v[20:21], v[96:97], v[118:119] op_sel:[0,1] op_sel_hi:[1,1]
	v_add_f32_dpp v12, v12, v12 quad_perm:[1,0,3,2] row_mask:0xf bank_mask:0xf bound_ctrl:1
	v_add_f32_dpp v13, v13, v13 quad_perm:[1,0,3,2] row_mask:0xf bank_mask:0xf bound_ctrl:1
	v_pk_fma_f32 v[18:19], v[2:3], v[86:87], v[18:19]
	v_add_f32_dpp v12, v12, v12 quad_perm:[2,3,0,1] row_mask:0xf bank_mask:0xf bound_ctrl:1
	v_add_f32_dpp v13, v13, v13 quad_perm:[2,3,0,1] row_mask:0xf bank_mask:0xf bound_ctrl:1
	v_pk_fma_f32 v[20:21], v[4:5], v[88:89], v[20:21]
	v_add_f32_dpp v12, v12, v12 row_half_mirror row_mask:0xf bank_mask:0xf bound_ctrl:1
	v_add_f32_dpp v13, v13, v13 row_half_mirror row_mask:0xf bank_mask:0xf bound_ctrl:1
	s_nop 0
	s_nop 0
	v_add_f32_dpp v12, v12, v12 row_mirror row_mask:0xf bank_mask:0xf bound_ctrl:1
	v_add_f32_dpp v13, v13, v13 row_mirror row_mask:0xf bank_mask:0xf bound_ctrl:1
	v_pk_fma_f32 v[2:3], v[90:91], v[12:13], v[18:19] op_sel_hi:[1,0,1]
	v_pk_fma_f32 v[4:5], v[92:93], v[12:13], v[20:21] op_sel_hi:[1,0,1]
	v_fmac_f32_e64 v13, v121, v12
	ds_write2_b32 v22, v11, v13 offset0:64 offset1:80
	ds_read_b128 v[58:61], v6 offset:30720
	ds_read_b128 v[62:65], v6 offset:30736
	ds_read_b128 v[66:69], v6 offset:30752
	ds_read_b128 v[70:73], v6 offset:30768
	ds_read_b128 v[74:77], v6 offset:30784
	ds_read2st64_b32 v[118:119], v7 offset0:24 offset1:25
	ds_read_b64 v[120:121], v8 offset:96
	s_waitcnt lgkmcnt(13)
	s_nop 0
	v_pk_mul_f32 v[14:15], v[2:3], v[98:99] op_sel_hi:[0,1]
	v_pk_fma_f32 v[14:15], v[2:3], v[100:101], v[14:15] op_sel:[1,0,0] op_sel_hi:[1,1,1]
	v_pk_fma_f32 v[14:15], v[4:5], v[102:103], v[14:15] op_sel_hi:[0,1,1]
	v_pk_fma_f32 v[14:15], v[4:5], v[104:105], v[14:15] op_sel:[1,0,0] op_sel_hi:[1,1,1]
	v_pk_mul_f32 v[18:19], v[114:115], v[206:207] op_sel_hi:[1,0]
	v_pk_mul_f32 v[20:21], v[116:117], v[206:207] op_sel_hi:[1,0]
	v_add_f32_dpp v14, v14, v14 quad_perm:[1,0,3,2] row_mask:0xf bank_mask:0xf bound_ctrl:1
	v_add_f32_dpp v15, v15, v15 quad_perm:[1,0,3,2] row_mask:0xf bank_mask:0xf bound_ctrl:1
	v_pk_fma_f32 v[18:19], v[2:3], v[106:107], v[18:19]
	v_add_f32_dpp v14, v14, v14 quad_perm:[2,3,0,1] row_mask:0xf bank_mask:0xf bound_ctrl:1
	v_add_f32_dpp v15, v15, v15 quad_perm:[2,3,0,1] row_mask:0xf bank_mask:0xf bound_ctrl:1
	v_pk_fma_f32 v[20:21], v[4:5], v[108:109], v[20:21]
	v_add_f32_dpp v14, v14, v14 row_half_mirror row_mask:0xf bank_mask:0xf bound_ctrl:1
	v_add_f32_dpp v15, v15, v15 row_half_mirror row_mask:0xf bank_mask:0xf bound_ctrl:1
	s_nop 0
	s_nop 0
	v_add_f32_dpp v14, v14, v14 row_mirror row_mask:0xf bank_mask:0xf bound_ctrl:1
	v_add_f32_dpp v15, v15, v15 row_mirror row_mask:0xf bank_mask:0xf bound_ctrl:1
	v_pk_fma_f32 v[2:3], v[110:111], v[14:15], v[18:19] op_sel_hi:[1,0,1]
	v_pk_fma_f32 v[4:5], v[112:113], v[14:15], v[20:21] op_sel_hi:[1,0,1]
	v_fmac_f32_e64 v15, v208, v14
	ds_read_b128 v[78:81], v6 offset:32000
	ds_read_b128 v[82:85], v6 offset:32016
	ds_read_b128 v[86:89], v6 offset:32032
	ds_read_b128 v[90:93], v6 offset:32048
	ds_read_b128 v[94:97], v6 offset:32064
	s_waitcnt lgkmcnt(13)
	s_nop 0
	v_pk_mul_f32 v[16:17], v[2:3], v[186:187] op_sel_hi:[0,1]
	v_pk_fma_f32 v[16:17], v[2:3], v[188:189], v[16:17] op_sel:[1,0,0] op_sel_hi:[1,1,1]
	v_pk_fma_f32 v[16:17], v[4:5], v[190:191], v[16:17] op_sel_hi:[0,1,1]
	v_pk_fma_f32 v[16:17], v[4:5], v[192:193], v[16:17] op_sel:[1,0,0] op_sel_hi:[1,1,1]
	v_pk_mul_f32 v[18:19], v[202:203], v[206:207] op_sel:[0,1] op_sel_hi:[1,1]
	v_pk_mul_f32 v[20:21], v[204:205], v[206:207] op_sel:[0,1] op_sel_hi:[1,1]
	v_add_f32_dpp v16, v16, v16 quad_perm:[1,0,3,2] row_mask:0xf bank_mask:0xf bound_ctrl:1
	v_add_f32_dpp v17, v17, v17 quad_perm:[1,0,3,2] row_mask:0xf bank_mask:0xf bound_ctrl:1
	v_pk_fma_f32 v[18:19], v[2:3], v[194:195], v[18:19]
	v_add_f32_dpp v16, v16, v16 quad_perm:[2,3,0,1] row_mask:0xf bank_mask:0xf bound_ctrl:1
	v_add_f32_dpp v17, v17, v17 quad_perm:[2,3,0,1] row_mask:0xf bank_mask:0xf bound_ctrl:1
	v_pk_fma_f32 v[20:21], v[4:5], v[196:197], v[20:21]
	v_add_f32_dpp v16, v16, v16 row_half_mirror row_mask:0xf bank_mask:0xf bound_ctrl:1
	v_add_f32_dpp v17, v17, v17 row_half_mirror row_mask:0xf bank_mask:0xf bound_ctrl:1
	s_nop 0
	s_nop 0
	v_add_f32_dpp v16, v16, v16 row_mirror row_mask:0xf bank_mask:0xf bound_ctrl:1
	v_add_f32_dpp v17, v17, v17 row_mirror row_mask:0xf bank_mask:0xf bound_ctrl:1
	v_pk_fma_f32 v[2:3], v[198:199], v[16:17], v[18:19] op_sel_hi:[1,0,1]
	v_pk_fma_f32 v[4:5], v[200:201], v[16:17], v[20:21] op_sel_hi:[1,0,1]
	v_fmac_f32_e64 v17, v209, v16
	ds_write2_b32 v22, v15, v17 offset0:96 offset1:112
	ds_read_b128 v[98:101], v6 offset:33280
	ds_read_b128 v[102:105], v6 offset:33296
	ds_read_b128 v[106:109], v6 offset:33312
	ds_read_b128 v[110:113], v6 offset:33328
	ds_read_b128 v[114:117], v6 offset:33344
	ds_read2st64_b32 v[206:207], v7 offset0:26 offset1:27
	ds_read_b64 v[208:209], v8 offset:104
	s_waitcnt lgkmcnt(13)
	s_nop 0
	v_pk_mul_f32 v[10:11], v[2:3], v[58:59] op_sel_hi:[0,1]
	v_pk_fma_f32 v[10:11], v[2:3], v[60:61], v[10:11] op_sel:[1,0,0] op_sel_hi:[1,1,1]
	v_pk_fma_f32 v[10:11], v[4:5], v[62:63], v[10:11] op_sel_hi:[0,1,1]
	v_pk_fma_f32 v[10:11], v[4:5], v[64:65], v[10:11] op_sel:[1,0,0] op_sel_hi:[1,1,1]
	v_pk_mul_f32 v[18:19], v[74:75], v[118:119] op_sel_hi:[1,0]
	v_pk_mul_f32 v[20:21], v[76:77], v[118:119] op_sel_hi:[1,0]
	v_add_f32_dpp v10, v10, v10 quad_perm:[1,0,3,2] row_mask:0xf bank_mask:0xf bound_ctrl:1
	v_add_f32_dpp v11, v11, v11 quad_perm:[1,0,3,2] row_mask:0xf bank_mask:0xf bound_ctrl:1
	v_pk_fma_f32 v[18:19], v[2:3], v[66:67], v[18:19]
	v_add_f32_dpp v10, v10, v10 quad_perm:[2,3,0,1] row_mask:0xf bank_mask:0xf bound_ctrl:1
	v_add_f32_dpp v11, v11, v11 quad_perm:[2,3,0,1] row_mask:0xf bank_mask:0xf bound_ctrl:1
	v_pk_fma_f32 v[20:21], v[4:5], v[68:69], v[20:21]
	v_add_f32_dpp v10, v10, v10 row_half_mirror row_mask:0xf bank_mask:0xf bound_ctrl:1
	v_add_f32_dpp v11, v11, v11 row_half_mirror row_mask:0xf bank_mask:0xf bound_ctrl:1
	s_nop 0
	s_nop 0
	v_add_f32_dpp v10, v10, v10 row_mirror row_mask:0xf bank_mask:0xf bound_ctrl:1
	v_add_f32_dpp v11, v11, v11 row_mirror row_mask:0xf bank_mask:0xf bound_ctrl:1
	v_pk_fma_f32 v[2:3], v[70:71], v[10:11], v[18:19] op_sel_hi:[1,0,1]
	v_pk_fma_f32 v[4:5], v[72:73], v[10:11], v[20:21] op_sel_hi:[1,0,1]
	v_fmac_f32_e64 v11, v120, v10
	ds_read_b128 v[186:189], v6 offset:34560
	ds_read_b128 v[190:193], v6 offset:34576
	ds_read_b128 v[194:197], v6 offset:34592
	ds_read_b128 v[198:201], v6 offset:34608
	ds_read_b128 v[202:205], v6 offset:34624
	s_waitcnt lgkmcnt(13)
	s_nop 0
	v_pk_mul_f32 v[12:13], v[2:3], v[78:79] op_sel_hi:[0,1]
	v_pk_fma_f32 v[12:13], v[2:3], v[80:81], v[12:13] op_sel:[1,0,0] op_sel_hi:[1,1,1]
	v_pk_fma_f32 v[12:13], v[4:5], v[82:83], v[12:13] op_sel_hi:[0,1,1]
	v_pk_fma_f32 v[12:13], v[4:5], v[84:85], v[12:13] op_sel:[1,0,0] op_sel_hi:[1,1,1]
	v_pk_mul_f32 v[18:19], v[94:95], v[118:119] op_sel:[0,1] op_sel_hi:[1,1]
	v_pk_mul_f32 v[20:21], v[96:97], v[118:119] op_sel:[0,1] op_sel_hi:[1,1]
	v_add_f32_dpp v12, v12, v12 quad_perm:[1,0,3,2] row_mask:0xf bank_mask:0xf bound_ctrl:1
	v_add_f32_dpp v13, v13, v13 quad_perm:[1,0,3,2] row_mask:0xf bank_mask:0xf bound_ctrl:1
	v_pk_fma_f32 v[18:19], v[2:3], v[86:87], v[18:19]
	v_add_f32_dpp v12, v12, v12 quad_perm:[2,3,0,1] row_mask:0xf bank_mask:0xf bound_ctrl:1
	v_add_f32_dpp v13, v13, v13 quad_perm:[2,3,0,1] row_mask:0xf bank_mask:0xf bound_ctrl:1
	v_pk_fma_f32 v[20:21], v[4:5], v[88:89], v[20:21]
	v_add_f32_dpp v12, v12, v12 row_half_mirror row_mask:0xf bank_mask:0xf bound_ctrl:1
	v_add_f32_dpp v13, v13, v13 row_half_mirror row_mask:0xf bank_mask:0xf bound_ctrl:1
	s_nop 0
	s_nop 0
	v_add_f32_dpp v12, v12, v12 row_mirror row_mask:0xf bank_mask:0xf bound_ctrl:1
	v_add_f32_dpp v13, v13, v13 row_mirror row_mask:0xf bank_mask:0xf bound_ctrl:1
	v_pk_fma_f32 v[2:3], v[90:91], v[12:13], v[18:19] op_sel_hi:[1,0,1]
	v_pk_fma_f32 v[4:5], v[92:93], v[12:13], v[20:21] op_sel_hi:[1,0,1]
	v_fmac_f32_e64 v13, v121, v12
	ds_write2_b32 v22, v11, v13 offset0:128 offset1:144
	ds_read_b128 v[58:61], v6 offset:35840
	ds_read_b128 v[62:65], v6 offset:35856
	ds_read_b128 v[66:69], v6 offset:35872
	ds_read_b128 v[70:73], v6 offset:35888
	ds_read_b128 v[74:77], v6 offset:35904
	ds_read2st64_b32 v[118:119], v7 offset0:28 offset1:29
	ds_read_b64 v[120:121], v8 offset:112
	s_waitcnt lgkmcnt(13)
	s_nop 0
	v_pk_mul_f32 v[14:15], v[2:3], v[98:99] op_sel_hi:[0,1]
	v_pk_fma_f32 v[14:15], v[2:3], v[100:101], v[14:15] op_sel:[1,0,0] op_sel_hi:[1,1,1]
	v_pk_fma_f32 v[14:15], v[4:5], v[102:103], v[14:15] op_sel_hi:[0,1,1]
	v_pk_fma_f32 v[14:15], v[4:5], v[104:105], v[14:15] op_sel:[1,0,0] op_sel_hi:[1,1,1]
	v_pk_mul_f32 v[18:19], v[114:115], v[206:207] op_sel_hi:[1,0]
	v_pk_mul_f32 v[20:21], v[116:117], v[206:207] op_sel_hi:[1,0]
	v_add_f32_dpp v14, v14, v14 quad_perm:[1,0,3,2] row_mask:0xf bank_mask:0xf bound_ctrl:1
	v_add_f32_dpp v15, v15, v15 quad_perm:[1,0,3,2] row_mask:0xf bank_mask:0xf bound_ctrl:1
	v_pk_fma_f32 v[18:19], v[2:3], v[106:107], v[18:19]
	v_add_f32_dpp v14, v14, v14 quad_perm:[2,3,0,1] row_mask:0xf bank_mask:0xf bound_ctrl:1
	v_add_f32_dpp v15, v15, v15 quad_perm:[2,3,0,1] row_mask:0xf bank_mask:0xf bound_ctrl:1
	v_pk_fma_f32 v[20:21], v[4:5], v[108:109], v[20:21]
	v_add_f32_dpp v14, v14, v14 row_half_mirror row_mask:0xf bank_mask:0xf bound_ctrl:1
	v_add_f32_dpp v15, v15, v15 row_half_mirror row_mask:0xf bank_mask:0xf bound_ctrl:1
	s_nop 0
	s_nop 0
	v_add_f32_dpp v14, v14, v14 row_mirror row_mask:0xf bank_mask:0xf bound_ctrl:1
	v_add_f32_dpp v15, v15, v15 row_mirror row_mask:0xf bank_mask:0xf bound_ctrl:1
	v_pk_fma_f32 v[2:3], v[110:111], v[14:15], v[18:19] op_sel_hi:[1,0,1]
	v_pk_fma_f32 v[4:5], v[112:113], v[14:15], v[20:21] op_sel_hi:[1,0,1]
	v_fmac_f32_e64 v15, v208, v14
	ds_read_b128 v[78:81], v6 offset:37120
	ds_read_b128 v[82:85], v6 offset:37136
	ds_read_b128 v[86:89], v6 offset:37152
	ds_read_b128 v[90:93], v6 offset:37168
	ds_read_b128 v[94:97], v6 offset:37184
	s_waitcnt lgkmcnt(13)
	s_nop 0
	v_pk_mul_f32 v[16:17], v[2:3], v[186:187] op_sel_hi:[0,1]
	v_pk_fma_f32 v[16:17], v[2:3], v[188:189], v[16:17] op_sel:[1,0,0] op_sel_hi:[1,1,1]
	v_pk_fma_f32 v[16:17], v[4:5], v[190:191], v[16:17] op_sel_hi:[0,1,1]
	v_pk_fma_f32 v[16:17], v[4:5], v[192:193], v[16:17] op_sel:[1,0,0] op_sel_hi:[1,1,1]
	v_pk_mul_f32 v[18:19], v[202:203], v[206:207] op_sel:[0,1] op_sel_hi:[1,1]
	v_pk_mul_f32 v[20:21], v[204:205], v[206:207] op_sel:[0,1] op_sel_hi:[1,1]
	v_add_f32_dpp v16, v16, v16 quad_perm:[1,0,3,2] row_mask:0xf bank_mask:0xf bound_ctrl:1
	v_add_f32_dpp v17, v17, v17 quad_perm:[1,0,3,2] row_mask:0xf bank_mask:0xf bound_ctrl:1
	v_pk_fma_f32 v[18:19], v[2:3], v[194:195], v[18:19]
	v_add_f32_dpp v16, v16, v16 quad_perm:[2,3,0,1] row_mask:0xf bank_mask:0xf bound_ctrl:1
	v_add_f32_dpp v17, v17, v17 quad_perm:[2,3,0,1] row_mask:0xf bank_mask:0xf bound_ctrl:1
	v_pk_fma_f32 v[20:21], v[4:5], v[196:197], v[20:21]
	v_add_f32_dpp v16, v16, v16 row_half_mirror row_mask:0xf bank_mask:0xf bound_ctrl:1
	v_add_f32_dpp v17, v17, v17 row_half_mirror row_mask:0xf bank_mask:0xf bound_ctrl:1
	s_nop 0
	s_nop 0
	v_add_f32_dpp v16, v16, v16 row_mirror row_mask:0xf bank_mask:0xf bound_ctrl:1
	v_add_f32_dpp v17, v17, v17 row_mirror row_mask:0xf bank_mask:0xf bound_ctrl:1
	v_pk_fma_f32 v[2:3], v[198:199], v[16:17], v[18:19] op_sel_hi:[1,0,1]
	v_pk_fma_f32 v[4:5], v[200:201], v[16:17], v[20:21] op_sel_hi:[1,0,1]
	v_fmac_f32_e64 v17, v209, v16
	ds_write2_b32 v22, v15, v17 offset0:160 offset1:176
	ds_read_b128 v[98:101], v6 offset:38400
	ds_read_b128 v[102:105], v6 offset:38416
	ds_read_b128 v[106:109], v6 offset:38432
	ds_read_b128 v[110:113], v6 offset:38448
	ds_read_b128 v[114:117], v6 offset:38464
	ds_read2st64_b32 v[206:207], v7 offset0:30 offset1:31
	ds_read_b64 v[208:209], v8 offset:120
	s_waitcnt lgkmcnt(13)
	s_nop 0
	v_pk_mul_f32 v[10:11], v[2:3], v[58:59] op_sel_hi:[0,1]
	v_pk_fma_f32 v[10:11], v[2:3], v[60:61], v[10:11] op_sel:[1,0,0] op_sel_hi:[1,1,1]
	v_pk_fma_f32 v[10:11], v[4:5], v[62:63], v[10:11] op_sel_hi:[0,1,1]
	v_pk_fma_f32 v[10:11], v[4:5], v[64:65], v[10:11] op_sel:[1,0,0] op_sel_hi:[1,1,1]
	v_pk_mul_f32 v[18:19], v[74:75], v[118:119] op_sel_hi:[1,0]
	v_pk_mul_f32 v[20:21], v[76:77], v[118:119] op_sel_hi:[1,0]
	v_add_f32_dpp v10, v10, v10 quad_perm:[1,0,3,2] row_mask:0xf bank_mask:0xf bound_ctrl:1
	v_add_f32_dpp v11, v11, v11 quad_perm:[1,0,3,2] row_mask:0xf bank_mask:0xf bound_ctrl:1
	v_pk_fma_f32 v[18:19], v[2:3], v[66:67], v[18:19]
	v_add_f32_dpp v10, v10, v10 quad_perm:[2,3,0,1] row_mask:0xf bank_mask:0xf bound_ctrl:1
	v_add_f32_dpp v11, v11, v11 quad_perm:[2,3,0,1] row_mask:0xf bank_mask:0xf bound_ctrl:1
	v_pk_fma_f32 v[20:21], v[4:5], v[68:69], v[20:21]
	v_add_f32_dpp v10, v10, v10 row_half_mirror row_mask:0xf bank_mask:0xf bound_ctrl:1
	v_add_f32_dpp v11, v11, v11 row_half_mirror row_mask:0xf bank_mask:0xf bound_ctrl:1
	s_nop 0
	s_nop 0
	v_add_f32_dpp v10, v10, v10 row_mirror row_mask:0xf bank_mask:0xf bound_ctrl:1
	v_add_f32_dpp v11, v11, v11 row_mirror row_mask:0xf bank_mask:0xf bound_ctrl:1
	v_pk_fma_f32 v[2:3], v[70:71], v[10:11], v[18:19] op_sel_hi:[1,0,1]
	v_pk_fma_f32 v[4:5], v[72:73], v[10:11], v[20:21] op_sel_hi:[1,0,1]
	v_fmac_f32_e64 v11, v120, v10
	ds_read_b128 v[186:189], v6 offset:39680
	ds_read_b128 v[190:193], v6 offset:39696
	ds_read_b128 v[194:197], v6 offset:39712
	ds_read_b128 v[198:201], v6 offset:39728
	ds_read_b128 v[202:205], v6 offset:39744
	s_waitcnt lgkmcnt(13)
	s_nop 0
	v_pk_mul_f32 v[12:13], v[2:3], v[78:79] op_sel_hi:[0,1]
	v_pk_fma_f32 v[12:13], v[2:3], v[80:81], v[12:13] op_sel:[1,0,0] op_sel_hi:[1,1,1]
	v_pk_fma_f32 v[12:13], v[4:5], v[82:83], v[12:13] op_sel_hi:[0,1,1]
	v_pk_fma_f32 v[12:13], v[4:5], v[84:85], v[12:13] op_sel:[1,0,0] op_sel_hi:[1,1,1]
	v_pk_mul_f32 v[18:19], v[94:95], v[118:119] op_sel:[0,1] op_sel_hi:[1,1]
	v_pk_mul_f32 v[20:21], v[96:97], v[118:119] op_sel:[0,1] op_sel_hi:[1,1]
	v_add_f32_dpp v12, v12, v12 quad_perm:[1,0,3,2] row_mask:0xf bank_mask:0xf bound_ctrl:1
	v_add_f32_dpp v13, v13, v13 quad_perm:[1,0,3,2] row_mask:0xf bank_mask:0xf bound_ctrl:1
	v_pk_fma_f32 v[18:19], v[2:3], v[86:87], v[18:19]
	v_add_f32_dpp v12, v12, v12 quad_perm:[2,3,0,1] row_mask:0xf bank_mask:0xf bound_ctrl:1
	v_add_f32_dpp v13, v13, v13 quad_perm:[2,3,0,1] row_mask:0xf bank_mask:0xf bound_ctrl:1
	v_pk_fma_f32 v[20:21], v[4:5], v[88:89], v[20:21]
	v_add_f32_dpp v12, v12, v12 row_half_mirror row_mask:0xf bank_mask:0xf bound_ctrl:1
	v_add_f32_dpp v13, v13, v13 row_half_mirror row_mask:0xf bank_mask:0xf bound_ctrl:1
	s_nop 0
	s_nop 0
	v_add_f32_dpp v12, v12, v12 row_mirror row_mask:0xf bank_mask:0xf bound_ctrl:1
	v_add_f32_dpp v13, v13, v13 row_mirror row_mask:0xf bank_mask:0xf bound_ctrl:1
	v_pk_fma_f32 v[2:3], v[90:91], v[12:13], v[18:19] op_sel_hi:[1,0,1]
	v_pk_fma_f32 v[4:5], v[92:93], v[12:13], v[20:21] op_sel_hi:[1,0,1]
	v_fmac_f32_e64 v13, v121, v12
	ds_write2_b32 v22, v11, v13 offset0:192 offset1:208
	s_waitcnt lgkmcnt(6)
	s_nop 0
	v_pk_mul_f32 v[14:15], v[2:3], v[98:99] op_sel_hi:[0,1]
	v_pk_fma_f32 v[14:15], v[2:3], v[100:101], v[14:15] op_sel:[1,0,0] op_sel_hi:[1,1,1]
	v_pk_fma_f32 v[14:15], v[4:5], v[102:103], v[14:15] op_sel_hi:[0,1,1]
	v_pk_fma_f32 v[14:15], v[4:5], v[104:105], v[14:15] op_sel:[1,0,0] op_sel_hi:[1,1,1]
	v_pk_mul_f32 v[18:19], v[114:115], v[206:207] op_sel_hi:[1,0]
	v_pk_mul_f32 v[20:21], v[116:117], v[206:207] op_sel_hi:[1,0]
	v_add_f32_dpp v14, v14, v14 quad_perm:[1,0,3,2] row_mask:0xf bank_mask:0xf bound_ctrl:1
	v_add_f32_dpp v15, v15, v15 quad_perm:[1,0,3,2] row_mask:0xf bank_mask:0xf bound_ctrl:1
	v_pk_fma_f32 v[18:19], v[2:3], v[106:107], v[18:19]
	v_add_f32_dpp v14, v14, v14 quad_perm:[2,3,0,1] row_mask:0xf bank_mask:0xf bound_ctrl:1
	v_add_f32_dpp v15, v15, v15 quad_perm:[2,3,0,1] row_mask:0xf bank_mask:0xf bound_ctrl:1
	v_pk_fma_f32 v[20:21], v[4:5], v[108:109], v[20:21]
	v_add_f32_dpp v14, v14, v14 row_half_mirror row_mask:0xf bank_mask:0xf bound_ctrl:1
	v_add_f32_dpp v15, v15, v15 row_half_mirror row_mask:0xf bank_mask:0xf bound_ctrl:1
	s_nop 0
	s_nop 0
	v_add_f32_dpp v14, v14, v14 row_mirror row_mask:0xf bank_mask:0xf bound_ctrl:1
	v_add_f32_dpp v15, v15, v15 row_mirror row_mask:0xf bank_mask:0xf bound_ctrl:1
	v_pk_fma_f32 v[2:3], v[110:111], v[14:15], v[18:19] op_sel_hi:[1,0,1]
	v_pk_fma_f32 v[4:5], v[112:113], v[14:15], v[20:21] op_sel_hi:[1,0,1]
	v_fmac_f32_e32 v15, v208, v14
	s_waitcnt lgkmcnt(1)
	v_pk_mul_f32 v[16:17], v[2:3], v[186:187] op_sel_hi:[0,1]
	v_pk_fma_f32 v[16:17], v[2:3], v[188:189], v[16:17] op_sel:[1,0,0] op_sel_hi:[1,1,1]
	v_pk_fma_f32 v[16:17], v[4:5], v[190:191], v[16:17] op_sel_hi:[0,1,1]
	v_pk_fma_f32 v[16:17], v[4:5], v[192:193], v[16:17] op_sel:[1,0,0] op_sel_hi:[1,1,1]
	v_pk_mul_f32 v[18:19], v[202:203], v[206:207] op_sel:[0,1] op_sel_hi:[1,1]
	v_pk_mul_f32 v[20:21], v[204:205], v[206:207] op_sel:[0,1] op_sel_hi:[1,1]
	v_add_f32_dpp v16, v16, v16 quad_perm:[1,0,3,2] row_mask:0xf bank_mask:0xf bound_ctrl:1
	v_add_f32_dpp v17, v17, v17 quad_perm:[1,0,3,2] row_mask:0xf bank_mask:0xf bound_ctrl:1
	v_pk_fma_f32 v[18:19], v[2:3], v[194:195], v[18:19]
	v_add_f32_dpp v16, v16, v16 quad_perm:[2,3,0,1] row_mask:0xf bank_mask:0xf bound_ctrl:1
	v_add_f32_dpp v17, v17, v17 quad_perm:[2,3,0,1] row_mask:0xf bank_mask:0xf bound_ctrl:1
	v_pk_fma_f32 v[20:21], v[4:5], v[196:197], v[20:21]
	v_add_f32_dpp v16, v16, v16 row_half_mirror row_mask:0xf bank_mask:0xf bound_ctrl:1
	v_add_f32_dpp v17, v17, v17 row_half_mirror row_mask:0xf bank_mask:0xf bound_ctrl:1
	s_nop 0
	s_nop 0
	v_add_f32_dpp v16, v16, v16 row_mirror row_mask:0xf bank_mask:0xf bound_ctrl:1
	v_add_f32_dpp v17, v17, v17 row_mirror row_mask:0xf bank_mask:0xf bound_ctrl:1
	v_pk_fma_f32 v[2:3], v[198:199], v[16:17], v[18:19] op_sel_hi:[1,0,1]
	v_pk_fma_f32 v[4:5], v[200:201], v[16:17], v[20:21] op_sel_hi:[1,0,1]
	v_fmac_f32_e64 v17, v209, v16
	ds_write2_b32 v22, v15, v17 offset0:224 offset1:240
	s_add_i32 s0, s0, 1
	s_cmpk_lg_i32 s0, 0x80
	s_waitcnt lgkmcnt(0)
	s_barrier
	s_cbranch_scc1 .LBB0_726
